# merge epilogue: gate rows of the 2nd/3rd row batches requested one batch early through renamed registers, counted vmcnt
# baseline (speedup 1.0000x reference)
; __device__ __forceinline__ float bf_lo(unsigned u) { return __uint_as_float(u << 16); }
; __device__ __forceinline__ float bf_hi(unsigned u) { return __uint_as_float(u & 0xffff0000u); }
; __device__ __forceinline__ u32x4 pack8(const f32x4 a, const f32x4 b) { u32x4 w; w.x = cvt_pk_bf16(a[0], a[1]); w.y = cvt_pk_bf16(a[2], a[3]); w.z = cvt_pk_bf16(b[0], b[1]); w.w = cvt_pk_bf16(b[2], b[3]); return w; }
;     __device__ __forceinline__ bool operator()(f32x4 (&acc)[2][2][4][2], const Unit& u, int wr, int wc, int fr, int fq) const {
;         const int row0 = u.pm * 256 + wr * 64 + fr, c0 = u.pn * 256 + wc * 32 + fq * 8;
;         const bf16_t* G = u.src == 0 ? RHO : SC;
;         float* pd = part + (size_t)u.src * MC * D - (size_t)ML * D;
; #pragma unroll
;         for (int b4 = 0; b4 < 4; ++b4) {
;             const int ai = b4 >> 1, mh = (b4 & 1) * 2;
;             u32x4 gq[2][2];
; #pragma unroll
;             for (int mm = 0; mm < 2; ++mm)
; #pragma unroll
;                 for (int bj = 0; bj < 2; ++bj) { const size_t ro = (size_t)(row0 + ai * 128 + (mh + mm) * 16) * D + c0 + bj * 128;
;                     gq[mm][bj] = *(const u32x4*)(G + ro); }
;             __builtin_amdgcn_sched_barrier(0);
; #pragma unroll
;             for (int mm = 0; mm < 2; ++mm)
; #pragma unroll
;                 for (int bj = 0; bj < 2; ++bj) { const size_t ro = (size_t)(row0 + ai * 128 + (mh + mm) * 16) * D + c0 + bj * 128; const int m = mh + mm;
;                     const u32x4 g = gq[mm][bj];
;                     f32x4 g0 = (f32x4){bf_lo(g.x), bf_hi(g.x), bf_lo(g.y), bf_hi(g.y)}, g1 = (f32x4){bf_lo(g.z), bf_hi(g.z), bf_lo(g.w), bf_hi(g.w)};
;                     if (u.src == 4) { const u32x4 r = *(const u32x4*)(RHO + ro);
;                         g0 *= (f32x4){bf_lo(r.x), bf_hi(r.x), bf_lo(r.y), bf_hi(r.y)}; g1 *= (f32x4){bf_lo(r.z), bf_hi(r.z), bf_lo(r.w), bf_hi(r.w)}; }
;                     acc[ai][bj][m][0] *= g0; acc[ai][bj][m][1] *= g1;
;                     if (u.src == 1) *(u32x4*)(Mo + ro) = pack8(acc[ai][bj][m][0], acc[ai][bj][m][1]);
;                     if (u.src >= 4) { *(f32x4*)(pd + ro) = acc[ai][bj][m][0]; *(f32x4*)(pd + ro + 4) = acc[ai][bj][m][1]; }
;                 }
.LBB0_231:
	s_cmp_lg_u32 s4, 0
	v_readlane_b32 s14, v253, 46
	s_cselect_b64 s[12:13], -1, 0
	s_cmp_eq_u32 s4, 0
	v_readlane_b32 s15, v253, 47
	v_lshl_add_u32 v152, s9, 8, v168
	v_lshl_or_b32 v150, s8, 8, v190
	s_cselect_b32 s8, s63, s15
	s_cselect_b32 s9, s62, s14
	v_mov_b32_e32 v128, s9
	v_mov_b32_e32 v129, s8
	v_ashrrev_i32_e32 v151, 31, v150
	v_ashrrev_i32_e32 v153, 31, v152
	v_lshl_add_u64 v[154:155], v[150:151], 1, v[128:129]
	v_lshlrev_b64 v[128:129], 12, v[152:153]
	v_or_b32_e32 v156, 16, v152
	v_lshl_add_u64 v[128:129], v[154:155], 0, v[128:129]
	v_ashrrev_i32_e32 v157, 31, v156
	global_load_dwordx4 v[182:185], v[128:129], off
	global_load_dwordx4 v[136:139], v[128:129], off offset:256
	v_lshlrev_b64 v[128:129], 12, v[156:157]
	v_lshl_add_u64 v[128:129], v[154:155], 0, v[128:129]
	global_load_dwordx4 v[132:135], v[128:129], off
	s_nop 0
	global_load_dwordx4 v[128:131], v[128:129], off offset:256
	v_or_b32_e32 v224, 32, v152
	v_ashrrev_i32_e32 v225, 31, v224
	v_lshlrev_b64 v[192:193], 12, v[224:225]
	v_or_b32_e32 v222, 48, v152
	v_lshl_add_u64 v[192:193], v[154:155], 0, v[192:193]
	v_ashrrev_i32_e32 v223, 31, v222
	global_load_dwordx4 v[204:207], v[192:193], off
	global_load_dwordx4 v[200:203], v[192:193], off offset:256
	v_lshlrev_b64 v[192:193], 12, v[222:223]
	v_lshl_add_u64 v[192:193], v[154:155], 0, v[192:193]
	global_load_dwordx4 v[196:199], v[192:193], off
	s_nop 0
	global_load_dwordx4 v[192:195], v[192:193], off offset:256
	v_lshlrev_b64 v[158:159], 11, v[152:153]
	s_cmp_eq_u32 s4, 4
	v_lshl_add_u64 v[158:159], v[158:159], 0, v[150:151]
	s_waitcnt vmcnt(4)
	v_lshlrev_b32_e32 v162, 16, v182
	v_and_b32_e32 v163, 0xffff0000, v182
	v_lshlrev_b32_e32 v166, 16, v183
	v_and_b32_e32 v167, 0xffff0000, v183
	v_lshlrev_b32_e32 v160, 16, v184
	v_and_b32_e32 v161, 0xffff0000, v184
	v_lshlrev_b32_e32 v164, 16, v185
	s_cselect_b64 s[34:35], -1, 0
	s_cmp_lg_u32 s4, 4
	v_and_b32_e32 v165, 0xffff0000, v185
	s_cbranch_scc1 .LBB0_233
	v_lshl_add_u64 v[178:179], v[158:159], 1, s[62:63]
	global_load_dwordx4 v[182:185], v[178:179], off
	s_waitcnt vmcnt(0)
	v_lshlrev_b32_e32 v178, 16, v182
	v_and_b32_e32 v179, 0xffff0000, v182
	v_lshlrev_b32_e32 v180, 16, v183
	v_and_b32_e32 v181, 0xffff0000, v183
	v_pk_mul_f32 v[166:167], v[166:167], v[180:181]
	v_pk_mul_f32 v[162:163], v[162:163], v[178:179]
	v_lshlrev_b32_e32 v178, 16, v184
	v_and_b32_e32 v179, 0xffff0000, v184
	v_lshlrev_b32_e32 v180, 16, v185
	v_and_b32_e32 v181, 0xffff0000, v185
	v_pk_mul_f32 v[164:165], v[164:165], v[180:181]
	v_pk_mul_f32 v[160:161], v[160:161], v[178:179]

; __device__ __forceinline__ float bf_lo(unsigned u) { return __uint_as_float(u << 16); }
; __device__ __forceinline__ float bf_hi(unsigned u) { return __uint_as_float(u & 0xffff0000u); }
; __device__ __forceinline__ u32x4 pack8(const f32x4 a, const f32x4 b) { u32x4 w; w.x = cvt_pk_bf16(a[0], a[1]); w.y = cvt_pk_bf16(a[2], a[3]); w.z = cvt_pk_bf16(b[0], b[1]); w.w = cvt_pk_bf16(b[2], b[3]); return w; }
;     __device__ __forceinline__ bool operator()(f32x4 (&acc)[2][2][4][2], const Unit& u, int wr, int wc, int fr, int fq) const {
;     ...
;         for (int b4 = 0; b4 < 4; ++b4) {
;             const int ai = b4 >> 1, mh = (b4 & 1) * 2;
;             u32x4 gq[2][2];
; #pragma unroll
;             for (int mm = 0; mm < 2; ++mm)
; #pragma unroll
;                 for (int bj = 0; bj < 2; ++bj) { const size_t ro = (size_t)(row0 + ai * 128 + (mh + mm) * 16) * D + c0 + bj * 128;
;                     gq[mm][bj] = *(const u32x4*)(G + ro); }
;             __builtin_amdgcn_sched_barrier(0);
; #pragma unroll
;             for (int mm = 0; mm < 2; ++mm)
; #pragma unroll
;                 for (int bj = 0; bj < 2; ++bj) { const size_t ro = (size_t)(row0 + ai * 128 + (mh + mm) * 16) * D + c0 + bj * 128; const int m = mh + mm;
;                     const u32x4 g = gq[mm][bj];
;                     f32x4 g0 = (f32x4){bf_lo(g.x), bf_hi(g.x), bf_lo(g.y), bf_hi(g.y)}, g1 = (f32x4){bf_lo(g.z), bf_hi(g.z), bf_lo(g.w), bf_hi(g.w)};
;                     if (u.src == 4) { const u32x4 r = *(const u32x4*)(RHO + ro);
;                         g0 *= (f32x4){bf_lo(r.x), bf_hi(r.x), bf_lo(r.y), bf_hi(r.y)}; g1 *= (f32x4){bf_lo(r.z), bf_hi(r.z), bf_lo(r.w), bf_hi(r.w)}; }
;                     acc[ai][bj][m][0] *= g0; acc[ai][bj][m][1] *= g1;
;                     if (u.src == 1) *(u32x4*)(Mo + ro) = pack8(acc[ai][bj][m][0], acc[ai][bj][m][1]);
;                     if (u.src >= 4) { *(f32x4*)(pd + ro) = acc[ai][bj][m][0]; *(f32x4*)(pd + ro + 4) = acc[ai][bj][m][1]; }
;                 }
.LBB0_255:
	v_add_u32_e32 v158, 0x80, v152
	v_ashrrev_i32_e32 v159, 31, v158
	v_lshlrev_b64 v[128:129], 12, v[158:159]
	v_add_u32_e32 v156, 0x90, v152
	v_lshl_add_u64 v[128:129], v[154:155], 0, v[128:129]
	v_ashrrev_i32_e32 v157, 31, v156
	global_load_dwordx4 v[182:185], v[128:129], off
	global_load_dwordx4 v[136:139], v[128:129], off offset:256
	v_lshlrev_b64 v[128:129], 12, v[156:157]
	v_lshl_add_u64 v[128:129], v[154:155], 0, v[128:129]
	global_load_dwordx4 v[132:135], v[128:129], off
	s_nop 0
	global_load_dwordx4 v[128:131], v[128:129], off offset:256
	v_lshlrev_b64 v[224:225], 11, v[224:225]
	v_cndmask_b32_e64 v153, 0, 1, s[34:35]
	v_lshl_add_u64 v[224:225], v[224:225], 0, v[150:151]
	s_waitcnt vmcnt(4)
	v_lshlrev_b32_e32 v228, 16, v204
	v_and_b32_e32 v229, 0xffff0000, v204
	v_lshlrev_b32_e32 v232, 16, v205
	v_and_b32_e32 v233, 0xffff0000, v205
	v_lshlrev_b32_e32 v226, 16, v206
	v_and_b32_e32 v227, 0xffff0000, v206
	v_lshlrev_b32_e32 v230, 16, v207
	v_cmp_ne_u32_e64 s[44:45], 1, v153
	s_andn2_b64 vcc, exec, s[34:35]
	v_and_b32_e32 v231, 0xffff0000, v207
	s_cbranch_vccnz .LBB0_257
	v_lshl_add_u64 v[178:179], v[224:225], 1, s[62:63]
	global_load_dwordx4 v[204:207], v[178:179], off
	s_waitcnt vmcnt(0)
	v_lshlrev_b32_e32 v178, 16, v204
	v_and_b32_e32 v179, 0xffff0000, v204
	v_lshlrev_b32_e32 v180, 16, v205
	v_and_b32_e32 v181, 0xffff0000, v205
	v_pk_mul_f32 v[232:233], v[232:233], v[180:181]
	v_pk_mul_f32 v[228:229], v[228:229], v[178:179]
	v_lshlrev_b32_e32 v178, 16, v206
	v_and_b32_e32 v179, 0xffff0000, v206
	v_lshlrev_b32_e32 v180, 16, v207
	v_and_b32_e32 v181, 0xffff0000, v207
	v_pk_mul_f32 v[230:231], v[230:231], v[180:181]
	v_pk_mul_f32 v[226:227], v[226:227], v[178:179]
.LBB0_257:
	v_pk_mul_f32 v[110:111], v[110:111], v[232:233]
	v_pk_mul_f32 v[108:109], v[108:109], v[228:229]
	v_pk_mul_f32 v[106:107], v[106:107], v[230:231]
	s_and_b64 vcc, exec, s[40:41]
	v_pk_mul_f32 v[104:105], v[104:105], v[226:227]
	s_cbranch_vccnz .LBB0_259
	v_lshl_add_u64 v[230:231], v[224:225], 1, s[80:81]
	v_cvt_pk_bf16_f32 v226, v108, v109
	v_cvt_pk_bf16_f32 v227, v110, v111
	v_cvt_pk_bf16_f32 v228, v104, v105
	v_cvt_pk_bf16_f32 v229, v106, v107
	global_store_dwordx4 v[230:231], v[226:229], off
.LBB0_259:
	s_and_b64 vcc, exec, s[42:43]
	s_mov_b64 s[8:9], 0
	s_cbranch_vccnz .LBB0_261
	v_lshl_add_u64 v[226:227], v[224:225], 2, s[18:19]
	s_mov_b64 s[8:9], s[34:35]
	global_store_dwordx4 v[226:227], v[108:111], off
	global_store_dwordx4 v[226:227], v[104:107], off offset:16
.LBB0_261:
	v_or_b32_e32 v224, 0x80, v224
	v_lshlrev_b32_e32 v226, 16, v200
	v_and_b32_e32 v227, 0xffff0000, v200
	v_lshlrev_b32_e32 v228, 16, v201
	v_and_b32_e32 v229, 0xffff0000, v201
	v_lshlrev_b32_e32 v200, 16, v202
	v_and_b32_e32 v201, 0xffff0000, v202
	v_lshlrev_b32_e32 v202, 16, v203
	s_andn2_b64 vcc, exec, s[8:9]
	v_and_b32_e32 v203, 0xffff0000, v203
	s_cbranch_vccnz .LBB0_263
	v_lshl_add_u64 v[230:231], v[224:225], 1, s[62:63]
	global_load_dwordx4 v[230:233], v[230:231], off
	s_waitcnt vmcnt(0)
	v_lshlrev_b32_e32 v178, 16, v230
	v_and_b32_e32 v179, 0xffff0000, v230
	v_lshlrev_b32_e32 v230, 16, v231
	v_and_b32_e32 v231, 0xffff0000, v231
	v_pk_mul_f32 v[228:229], v[228:229], v[230:231]
	v_lshlrev_b32_e32 v230, 16, v232
	v_and_b32_e32 v231, 0xffff0000, v232
	v_lshlrev_b32_e32 v232, 16, v233
	v_and_b32_e32 v233, 0xffff0000, v233
	v_pk_mul_f32 v[226:227], v[226:227], v[178:179]
	v_pk_mul_f32 v[202:203], v[202:203], v[232:233]
	v_pk_mul_f32 v[200:201], v[200:201], v[230:231]
.LBB0_263:
	v_pk_mul_f32 v[78:79], v[78:79], v[228:229]
	v_pk_mul_f32 v[76:77], v[76:77], v[226:227]
	v_pk_mul_f32 v[74:75], v[74:75], v[202:203]
	s_and_b64 vcc, exec, s[40:41]
	v_pk_mul_f32 v[72:73], v[72:73], v[200:201]
	s_cbranch_vccnz .LBB0_265
	v_lshl_add_u64 v[226:227], v[224:225], 1, s[80:81]
	v_cvt_pk_bf16_f32 v200, v76, v77
	v_cvt_pk_bf16_f32 v201, v78, v79
	v_cvt_pk_bf16_f32 v202, v72, v73
	v_cvt_pk_bf16_f32 v203, v74, v75
	global_store_dwordx4 v[226:227], v[200:203], off
.LBB0_265:
	s_and_b64 vcc, exec, s[42:43]
	s_mov_b64 s[8:9], 0
	s_cbranch_vccnz .LBB0_267
	v_lshl_add_u64 v[200:201], v[224:225], 2, s[18:19]
	s_mov_b64 s[8:9], s[34:35]
	global_store_dwordx4 v[200:201], v[76:79], off
	global_store_dwordx4 v[200:201], v[72:75], off offset:16
; __device__ __forceinline__ float bf_lo(unsigned u) { return __uint_as_float(u << 16); }
; __device__ __forceinline__ float bf_hi(unsigned u) { return __uint_as_float(u & 0xffff0000u); }
; __device__ __forceinline__ u32x4 pack8(const f32x4 a, const f32x4 b) { u32x4 w; w.x = cvt_pk_bf16(a[0], a[1]); w.y = cvt_pk_bf16(a[2], a[3]); w.z = cvt_pk_bf16(b[0], b[1]); w.w = cvt_pk_bf16(b[2], b[3]); return w; }
;     __device__ __forceinline__ bool operator()(f32x4 (&acc)[2][2][4][2], const Unit& u, int wr, int wc, int fr, int fq) const {
;     ...
;         for (int b4 = 0; b4 < 4; ++b4) {
;             const int ai = b4 >> 1, mh = (b4 & 1) * 2;
;             u32x4 gq[2][2];
; #pragma unroll
;             for (int mm = 0; mm < 2; ++mm)
; #pragma unroll
;                 for (int bj = 0; bj < 2; ++bj) { const size_t ro = (size_t)(row0 + ai * 128 + (mh + mm) * 16) * D + c0 + bj * 128;
;                     gq[mm][bj] = *(const u32x4*)(G + ro); }
;             __builtin_amdgcn_sched_barrier(0);
; #pragma unroll
;             for (int mm = 0; mm < 2; ++mm)
; #pragma unroll
;                 for (int bj = 0; bj < 2; ++bj) { const size_t ro = (size_t)(row0 + ai * 128 + (mh + mm) * 16) * D + c0 + bj * 128; const int m = mh + mm;
;                     const u32x4 g = gq[mm][bj];
;                     f32x4 g0 = (f32x4){bf_lo(g.x), bf_hi(g.x), bf_lo(g.y), bf_hi(g.y)}, g1 = (f32x4){bf_lo(g.z), bf_hi(g.z), bf_lo(g.w), bf_hi(g.w)};
;                     if (u.src == 4) { const u32x4 r = *(const u32x4*)(RHO + ro);
;                         g0 *= (f32x4){bf_lo(r.x), bf_hi(r.x), bf_lo(r.y), bf_hi(r.y)}; g1 *= (f32x4){bf_lo(r.z), bf_hi(r.z), bf_lo(r.w), bf_hi(r.w)}; }
;                     acc[ai][bj][m][0] *= g0; acc[ai][bj][m][1] *= g1;
;                     if (u.src == 1) *(u32x4*)(Mo + ro) = pack8(acc[ai][bj][m][0], acc[ai][bj][m][1]);
;                     if (u.src >= 4) { *(f32x4*)(pd + ro) = acc[ai][bj][m][0]; *(f32x4*)(pd + ro + 4) = acc[ai][bj][m][1]; }
;                 }
.LBB0_267:
	v_lshlrev_b64 v[200:201], 11, v[222:223]
	v_lshl_add_u64 v[200:201], v[200:201], 0, v[150:151]
	v_lshlrev_b32_e32 v202, 16, v196
	v_and_b32_e32 v203, 0xffff0000, v196
	v_lshlrev_b32_e32 v222, 16, v197
	v_and_b32_e32 v223, 0xffff0000, v197
	v_lshlrev_b32_e32 v196, 16, v198
	v_and_b32_e32 v197, 0xffff0000, v198
	v_lshlrev_b32_e32 v198, 16, v199
	s_andn2_b64 vcc, exec, s[8:9]
	v_and_b32_e32 v199, 0xffff0000, v199
	s_cbranch_vccnz .LBB0_269
	v_lshl_add_u64 v[224:225], v[200:201], 1, s[62:63]
	global_load_dwordx4 v[224:227], v[224:225], off
	s_waitcnt vmcnt(0)
	v_lshlrev_b32_e32 v228, 16, v224
	v_and_b32_e32 v229, 0xffff0000, v224
	v_lshlrev_b32_e32 v224, 16, v225
	v_and_b32_e32 v225, 0xffff0000, v225
	v_pk_mul_f32 v[222:223], v[222:223], v[224:225]
	v_lshlrev_b32_e32 v224, 16, v226
	v_and_b32_e32 v225, 0xffff0000, v226
	v_lshlrev_b32_e32 v226, 16, v227
	v_and_b32_e32 v227, 0xffff0000, v227
	v_pk_mul_f32 v[202:203], v[202:203], v[228:229]
	v_pk_mul_f32 v[198:199], v[198:199], v[226:227]
	v_pk_mul_f32 v[196:197], v[196:197], v[224:225]
.LBB0_269:
	v_pk_mul_f32 v[102:103], v[102:103], v[222:223]
	v_pk_mul_f32 v[100:101], v[100:101], v[202:203]
	v_pk_mul_f32 v[98:99], v[98:99], v[198:199]
	s_and_b64 vcc, exec, s[40:41]
	v_pk_mul_f32 v[96:97], v[96:97], v[196:197]
	s_cbranch_vccnz .LBB0_271
	v_lshl_add_u64 v[202:203], v[200:201], 1, s[80:81]
	v_cvt_pk_bf16_f32 v196, v100, v101
	v_cvt_pk_bf16_f32 v197, v102, v103
	v_cvt_pk_bf16_f32 v198, v96, v97
	v_cvt_pk_bf16_f32 v199, v98, v99
	global_store_dwordx4 v[202:203], v[196:199], off
.LBB0_271:
	s_and_b64 vcc, exec, s[42:43]
	s_mov_b64 s[8:9], 0
	s_cbranch_vccnz .LBB0_273
	v_lshl_add_u64 v[196:197], v[200:201], 2, s[18:19]
	s_mov_b64 s[8:9], s[34:35]
	global_store_dwordx4 v[196:197], v[100:103], off
	global_store_dwordx4 v[196:197], v[96:99], off offset:16
.LBB0_273:
	v_or_b32_e32 v200, 0x80, v200
	v_lshlrev_b32_e32 v196, 16, v192
	v_and_b32_e32 v197, 0xffff0000, v192
	v_lshlrev_b32_e32 v198, 16, v193
	v_and_b32_e32 v199, 0xffff0000, v193
	v_lshlrev_b32_e32 v192, 16, v194
	v_and_b32_e32 v193, 0xffff0000, v194
	v_lshlrev_b32_e32 v194, 16, v195
	s_andn2_b64 vcc, exec, s[8:9]
	v_and_b32_e32 v195, 0xffff0000, v195
	s_cbranch_vccnz .LBB0_275
	v_lshl_add_u64 v[202:203], v[200:201], 1, s[62:63]
	global_load_dwordx4 v[222:225], v[202:203], off
	s_waitcnt vmcnt(0)
	v_lshlrev_b32_e32 v202, 16, v222
	v_and_b32_e32 v203, 0xffff0000, v222
	v_lshlrev_b32_e32 v222, 16, v223
	v_and_b32_e32 v223, 0xffff0000, v223
	v_pk_mul_f32 v[198:199], v[198:199], v[222:223]
	v_pk_mul_f32 v[196:197], v[196:197], v[202:203]
	v_lshlrev_b32_e32 v202, 16, v224
	v_and_b32_e32 v203, 0xffff0000, v224
	v_lshlrev_b32_e32 v222, 16, v225
	v_and_b32_e32 v223, 0xffff0000, v225
	v_pk_mul_f32 v[194:195], v[194:195], v[222:223]
	v_pk_mul_f32 v[192:193], v[192:193], v[202:203]
.LBB0_275:
	v_pk_mul_f32 v[70:71], v[70:71], v[198:199]
	v_pk_mul_f32 v[68:69], v[68:69], v[196:197]
	v_pk_mul_f32 v[66:67], v[66:67], v[194:195]
	s_and_b64 vcc, exec, s[40:41]
	v_pk_mul_f32 v[64:65], v[64:65], v[192:193]
	s_cbranch_vccnz .LBB0_277
	v_lshl_add_u64 v[196:197], v[200:201], 1, s[80:81]
	v_cvt_pk_bf16_f32 v192, v68, v69
	v_cvt_pk_bf16_f32 v193, v70, v71
	v_cvt_pk_bf16_f32 v194, v64, v65
	v_cvt_pk_bf16_f32 v195, v66, v67
	global_store_dwordx4 v[196:197], v[192:195], off
.LBB0_277:
	s_and_b64 vcc, exec, s[42:43]
	s_cbranch_vccnz .LBB0_279
	v_lshl_add_u64 v[192:193], v[200:201], 2, s[18:19]
	global_store_dwordx4 v[192:193], v[68:71], off
	global_store_dwordx4 v[192:193], v[64:67], off offset:16
.LBB0_279:
	v_lshlrev_b64 v[158:159], 11, v[158:159]
	v_lshl_add_u64 v[158:159], v[158:159], 0, v[150:151]
	s_waitcnt vmcnt(0)
	v_lshlrev_b32_e32 v162, 16, v182
	v_and_b32_e32 v163, 0xffff0000, v182
	v_lshlrev_b32_e32 v166, 16, v183
	v_and_b32_e32 v167, 0xffff0000, v183
	v_lshlrev_b32_e32 v160, 16, v184
	v_and_b32_e32 v161, 0xffff0000, v184
	v_lshlrev_b32_e32 v164, 16, v185
	s_and_b64 vcc, exec, s[44:45]
	v_and_b32_e32 v165, 0xffff0000, v185
	s_cbranch_vccnz .LBB0_281
	v_lshl_add_u64 v[178:179], v[158:159], 1, s[62:63]
	global_load_dwordx4 v[182:185], v[178:179], off
	s_waitcnt vmcnt(0)
	v_lshlrev_b32_e32 v178, 16, v182
	v_and_b32_e32 v179, 0xffff0000, v182
	v_lshlrev_b32_e32 v180, 16, v183
	v_and_b32_e32 v181, 0xffff0000, v183
	v_pk_mul_f32 v[166:167], v[166:167], v[180:181]
	v_pk_mul_f32 v[162:163], v[162:163], v[178:179]
	v_lshlrev_b32_e32 v178, 16, v184
	v_and_b32_e32 v179, 0xffff0000, v184
	v_lshlrev_b32_e32 v180, 16, v185
	v_and_b32_e32 v181, 0xffff0000, v185
	v_pk_mul_f32 v[164:165], v[164:165], v[180:181]
	v_pk_mul_f32 v[160:161], v[160:161], v[178:179]
